# FFN-up and Res GEMM tile set-up: removed the conservative s_waitcnt vmcnt(0) inside the accumulator zeroing (epilogue store acks and next-tile DMA now overlap the set-up; the K-loop's counted waits al
# speedup vs baseline: 1.0057x; 1.0057x over previous
.LBB0_134:
	s_ashr_i32 s47, s46, 31
	s_lshl_b64 s[6:7], s[46:47], 19
	s_add_u32 s48, s92, s6
	s_addc_u32 s49, s93, s7
	s_and_b64 s[6:7], s[38:39], exec
	s_cselect_b32 s47, s49, s53
	s_cselect_b32 s68, s48, s52
	s_ashr_i32 s45, s44, 31
	s_lshl_b64 s[6:7], s[44:45], 19
	s_add_u32 s50, s58, s6
	s_addc_u32 s51, s59, s7
	s_and_b64 s[6:7], s[38:39], exec
	s_cselect_b32 s45, s51, s55
	s_cselect_b32 s69, s50, s54
	s_add_u32 s52, s52, 0x40080
	s_addc_u32 s53, s53, 0
	s_add_u32 s70, s54, 0x100
	v_mov_b32_e32 v2, 0
	s_addc_u32 s71, s55, 0
	s_mov_b32 s72, -2
	v_mov_b32_e32 v3, v2
	v_mov_b64_e32 v[4:5], 0
	v_mov_b64_e32 v[6:7], 0
	v_mov_b64_e32 v[8:9], 0
	v_mov_b64_e32 v[18:19], 0
	v_mov_b64_e32 v[20:21], 0
	v_mov_b64_e32 v[22:23], 0
	v_mov_b64_e32 v[24:25], 0
	v_mov_b64_e32 v[34:35], 0
	v_mov_b64_e32 v[36:37], 0
	v_mov_b64_e32 v[38:39], 0
	v_mov_b64_e32 v[40:41], 0
	v_mov_b64_e32 v[50:51], 0
	v_mov_b64_e32 v[52:53], 0
	v_mov_b64_e32 v[54:55], 0
	v_mov_b64_e32 v[56:57], 0
	v_mov_b64_e32 v[10:11], 0
	v_mov_b64_e32 v[12:13], 0
	v_mov_b64_e32 v[14:15], 0
	v_mov_b64_e32 v[16:17], 0
	v_mov_b64_e32 v[26:27], 0
	v_mov_b64_e32 v[28:29], 0
	v_mov_b64_e32 v[30:31], 0
	v_mov_b64_e32 v[32:33], 0
	v_mov_b64_e32 v[42:43], 0
	v_mov_b64_e32 v[44:45], 0
	v_mov_b64_e32 v[46:47], 0
	v_mov_b64_e32 v[48:49], 0
	v_mov_b64_e32 v[58:59], 0
	v_mov_b64_e32 v[60:61], 0
	v_mov_b64_e32 v[62:63], 0
	v_mov_b64_e32 v[64:65], 0
	v_mov_b64_e32 v[66:67], 0
	v_mov_b64_e32 v[68:69], 0
	v_mov_b64_e32 v[70:71], 0
	v_mov_b64_e32 v[72:73], 0
	v_mov_b64_e32 v[82:83], 0
	v_mov_b64_e32 v[84:85], 0
	v_mov_b64_e32 v[86:87], 0
	v_mov_b64_e32 v[88:89], 0
	v_mov_b64_e32 v[98:99], 0
	v_mov_b64_e32 v[100:101], 0
	v_mov_b64_e32 v[102:103], 0
	v_mov_b64_e32 v[104:105], 0
	v_mov_b64_e32 v[114:115], 0
	v_mov_b64_e32 v[116:117], 0
	v_mov_b64_e32 v[118:119], 0
	v_mov_b64_e32 v[120:121], 0
	v_mov_b64_e32 v[74:75], 0
	v_mov_b64_e32 v[76:77], 0
	v_mov_b64_e32 v[78:79], 0
	v_mov_b64_e32 v[80:81], 0
	v_mov_b64_e32 v[90:91], 0
	v_mov_b64_e32 v[92:93], 0
	v_mov_b64_e32 v[94:95], 0
	v_mov_b64_e32 v[96:97], 0
	v_mov_b64_e32 v[106:107], 0
	v_mov_b64_e32 v[108:109], 0
	v_mov_b64_e32 v[110:111], 0
	v_mov_b64_e32 v[112:113], 0
	v_mov_b64_e32 v[122:123], 0
	v_mov_b64_e32 v[124:125], 0
	v_mov_b64_e32 v[126:127], 0
	v_mov_b64_e32 v[128:129], 0

.LBB0_762:
	s_add_u32 s50, s50, 0x80
	s_addc_u32 s51, s51, 0
	s_add_u32 s37, s52, 0x100
	v_mov_b32_e32 v2, 0
	s_addc_u32 s54, s53, 0
	s_mov_b32 s24, 0
	v_mov_b32_e32 v3, v2
	v_mov_b64_e32 v[4:5], 0
	s_waitcnt lgkmcnt(0)
	v_mov_b64_e32 v[6:7], 0
	v_mov_b64_e32 v[8:9], 0
	v_mov_b64_e32 v[18:19], 0
	v_mov_b64_e32 v[20:21], 0
	v_mov_b64_e32 v[22:23], 0
	v_mov_b64_e32 v[24:25], 0
	v_mov_b64_e32 v[34:35], 0
	v_mov_b64_e32 v[36:37], 0
	v_mov_b64_e32 v[38:39], 0
	v_mov_b64_e32 v[40:41], 0
	v_mov_b64_e32 v[50:51], 0
	v_mov_b64_e32 v[52:53], 0
	v_mov_b64_e32 v[54:55], 0
	v_mov_b64_e32 v[56:57], 0
	v_mov_b64_e32 v[10:11], 0
	v_mov_b64_e32 v[12:13], 0
	v_mov_b64_e32 v[14:15], 0
	v_mov_b64_e32 v[16:17], 0
	v_mov_b64_e32 v[26:27], 0
	v_mov_b64_e32 v[28:29], 0
	v_mov_b64_e32 v[30:31], 0
	v_mov_b64_e32 v[32:33], 0
	v_mov_b64_e32 v[42:43], 0
	v_mov_b64_e32 v[44:45], 0
	v_mov_b64_e32 v[46:47], 0
	v_mov_b64_e32 v[48:49], 0
	v_mov_b64_e32 v[58:59], 0
	v_mov_b64_e32 v[60:61], 0
	v_mov_b64_e32 v[62:63], 0
	v_mov_b64_e32 v[64:65], 0
	v_mov_b64_e32 v[66:67], 0
	v_mov_b64_e32 v[68:69], 0
	v_mov_b64_e32 v[70:71], 0
	v_mov_b64_e32 v[72:73], 0
	v_mov_b64_e32 v[82:83], 0
	v_mov_b64_e32 v[84:85], 0
	v_mov_b64_e32 v[86:87], 0
	v_mov_b64_e32 v[88:89], 0
	v_mov_b64_e32 v[98:99], 0
	v_mov_b64_e32 v[100:101], 0
	v_mov_b64_e32 v[102:103], 0
	v_mov_b64_e32 v[104:105], 0
	v_mov_b64_e32 v[114:115], 0
	v_mov_b64_e32 v[116:117], 0
	v_mov_b64_e32 v[118:119], 0
	v_mov_b64_e32 v[120:121], 0
	v_mov_b64_e32 v[74:75], 0
	v_mov_b64_e32 v[76:77], 0
	v_mov_b64_e32 v[78:79], 0
	v_mov_b64_e32 v[80:81], 0
	v_mov_b64_e32 v[90:91], 0
	v_mov_b64_e32 v[92:93], 0
	v_mov_b64_e32 v[94:95], 0
	v_mov_b64_e32 v[96:97], 0
	v_mov_b64_e32 v[106:107], 0
	v_mov_b64_e32 v[108:109], 0
	v_mov_b64_e32 v[110:111], 0
	v_mov_b64_e32 v[112:113], 0
	v_mov_b64_e32 v[126:127], 0
	v_mov_b64_e32 v[128:129], 0
	v_mov_b64_e32 v[130:131], 0
	v_mov_b64_e32 v[132:133], 0
